# P6 chunk scan: the streaming record loads (read once) marked nt so they do not displace reusable data in L2 / MALL
# speedup vs baseline: 1.0202x; 1.0003x over previous
.LBB0_1129:
	s_or_b64 exec, exec, s[0:1]
	s_waitcnt lgkmcnt(0)
	v_readlane_b32 s0, v244, 24
	v_readlane_b32 s1, v244, 25
	s_add_u32 s42, s0, 0x24c00000
	s_addc_u32 s43, s1, 0
	v_readlane_b32 s0, v244, 0
	s_cmp_lt_i32 s0, 64
	s_waitcnt lgkmcnt(0)
	s_barrier
	v_readlane_b32 s1, v244, 1
	s_mov_b32 s101, 0x20400
	v_and_b32_e32 v246, 0x3ff, v0
	v_cmp_lt_u32_e32 vcc, 0x80, v246
	s_nop 1
	v_cndmask_b32_e64 v247, 0, 1, vcc
	v_cmp_lt_u32_e32 vcc, 0x101, v246
	s_nop 1
	v_cndmask_b32_e64 v248, 0, 1, vcc
	v_add_u32_e32 v247, v247, v248
	v_mul_u32_u24_e32 v249, 0x81, v247
	v_sub_u32_e32 v249, v246, v249
	v_lshlrev_b32_e32 v250, 1, v247
	v_lshlrev_b32_e32 v249, v250, v249
	v_min_u32_e32 v251, 1, v247
	v_add_u32_e32 v251, v249, v251
	v_max_u32_e32 v251, 32, v251
	v_min_u32_e32 v251, 0x81, v251
	v_subrev_u32_e32 v251, 32, v251
	v_add_u32_e32 v252, v249, v248
	v_add_u32_e32 v252, 3, v252
	v_lshrrev_b32_e32 v252, 2, v252
	v_min_u32_e32 v252, 0x81, v252
	v_add_u32_e32 v253, 15, v249
	v_lshrrev_b32_e32 v253, 4, v253
	v_min_u32_e32 v253, 0x81, v253
	v_add3_u32 v251, v251, v252, v253
	v_add_u32_e32 v251, 32, v251
	v_cmp_gt_u32_e32 vcc, 32, v246
	s_nop 1
	v_cndmask_b32_e32 v251, v251, v246, vcc
	v_cmp_lt_u32_e32 vcc, 0x182, v246
	s_nop 1
	v_cndmask_b32_e32 v251, v251, v246, vcc
	v_cmp_gt_u32_e32 vcc, 0x188, v246
	s_and_saveexec_b64 s[98:99], vcc
	v_lshl_add_u32 v252, v251, 2, s101
	ds_write_b32 v252, v246
	s_or_b64 exec, exec, s[98:99]
	s_waitcnt lgkmcnt(0)
	s_barrier
	s_cmp_lt_i32 s0, 64
	s_cbranch_scc0 .LBB0_1220
	v_mov_b32_e32 v114, v0
	v_readlane_b32 s0, v245, 39
	v_lshlrev_b32_e32 v2, 2, v114
	v_and_b32_e32 v112, 60, v2
	v_lshlrev_b32_e32 v86, 2, v112
	v_readlane_b32 s2, v245, 41
	v_readlane_b32 s3, v245, 42
	s_barrier
	v_readlane_b32 s1, v245, 40
	v_readfirstlane_b32 s0, v114
	s_nop 1
	global_load_dwordx4 v[66:69], v86, s[2:3] nt
	s_ashr_i32 s26, s0, 6
	v_readlane_b32 s0, v244, 0
	v_readlane_b32 s1, v244, 1
	s_mov_b32 s2, s0
	s_ashr_i32 s3, s0, 31
	s_ashr_i32 s35, s0, 3
	s_and_b32 s27, s0, 7
	v_writelane_b32 v244, s2, 0
	s_mul_i32 s1, s2, 0x168000
	s_mul_hi_i32 s0, s0, 0x168000
	s_add_u32 s30, s44, s1
	s_addc_u32 s31, s45, s0
	s_add_i32 s34, s26, -2
	v_add_u32_e32 v104, 0xffffff80, v114
	s_cmp_gt_u32 s34, 2
	v_mov_b32_e32 v83, 0
	v_readlane_b32 s4, v245, 43
	v_readlane_b32 s5, v245, 44
	v_readlane_b32 s6, v245, 45
	v_readlane_b32 s7, v245, 46
	v_readlane_b32 s8, v245, 47
	v_readlane_b32 s9, v245, 48
	v_readlane_b32 s10, v245, 49
	v_readlane_b32 s11, v245, 50
	v_readlane_b32 s12, v245, 51
	v_readlane_b32 s13, v245, 52
	v_readlane_b32 s14, v245, 53
	v_readlane_b32 s15, v245, 54
	v_writelane_b32 v244, s3, 1
	s_cbranch_scc1 .LBB0_1152
	v_min_i32_e32 v2, 0x59f, v104
	v_ashrrev_i32_e32 v3, 31, v2
	v_lshlrev_b64 v[84:85], 4, v[2:3]
	v_min_i32_e32 v2, 0x4df, v104
	v_ashrrev_i32_e32 v3, 31, v2
	v_mov_b64_e32 v[4:5], 0xc00
	v_min_i32_e32 v6, 0x41f, v104
	v_lshl_add_u64 v[2:3], v[2:3], 4, v[4:5]
	v_ashrrev_i32_e32 v7, 31, v6
	v_mov_b64_e32 v[8:9], 0x1800
	v_lshl_add_u64 v[4:5], s[30:31], 0, v[2:3]
	v_lshl_add_u64 v[6:7], v[6:7], 4, v[8:9]
	v_lshl_add_u64 v[8:9], s[30:31], 0, v[6:7]
	global_load_dwordx4 v[74:77], v[4:5], off nt
	global_load_dwordx4 v[54:57], v[8:9], off nt
	v_min_i32_e32 v4, 0x35f, v104
	v_ashrrev_i32_e32 v5, 31, v4
	v_mov_b64_e32 v[8:9], 0x2400
	v_min_i32_e32 v10, 0x29f, v104
	v_lshl_add_u64 v[4:5], v[4:5], 4, v[8:9]
	v_ashrrev_i32_e32 v11, 31, v10
	v_mov_b64_e32 v[12:13], 0x3000
	s_lshl_b32 s0, s35, 11
	v_lshl_add_u64 v[8:9], s[30:31], 0, v[4:5]
	v_lshl_add_u64 v[10:11], v[10:11], 4, v[12:13]
	s_ashr_i32 s1, s0, 31
	v_lshl_add_u64 v[12:13], s[30:31], 0, v[10:11]
	global_load_dwordx4 v[62:65], v[8:9], off nt
	global_load_dwordx4 v[46:49], v[12:13], off nt
	v_min_i32_e32 v8, 0x1df, v104
	s_lshl_b64 s[2:3], s[0:1], 12
	v_ashrrev_i32_e32 v9, 31, v8
	v_mov_b64_e32 v[12:13], 0x3c00
	v_min_i32_e32 v14, 0x11f, v104
	s_add_u32 s1, s64, s2
	v_lshl_add_u64 v[8:9], v[8:9], 4, v[12:13]
	v_ashrrev_i32_e32 v15, 31, v14
	v_mov_b64_e32 v[16:17], 0x4800
	v_min_i32_e32 v20, 0xff, v104
	s_addc_u32 s3, s65, s3
	v_lshl_add_u64 v[12:13], s[30:31], 0, v[8:9]
	v_lshl_add_u64 v[14:15], v[14:15], 4, v[16:17]
	s_lshl_b32 s4, s27, 7
	v_ashrrev_i32_e32 v18, 3, v20
	v_lshl_add_u64 v[16:17], s[30:31], 0, v[14:15]
	global_load_dwordx4 v[58:61], v[12:13], off nt
	global_load_dwordx4 v[42:45], v[16:17], off nt
	v_min_i32_e32 v12, 0x5f, v104
	s_add_u32 s2, s1, s4
	v_ashrrev_i32_e32 v19, 31, v18
	v_ashrrev_i32_e32 v13, 31, v12
	v_mov_b64_e32 v[16:17], 0x5400
	s_addc_u32 s3, s3, 0
	v_lshlrev_b64 v[88:89], 12, v[18:19]
	v_lshlrev_b32_e32 v20, 4, v20
	v_lshl_add_u64 v[12:13], v[12:13], 4, v[16:17]
	v_lshl_add_u64 v[18:19], s[2:3], 0, v[88:89]
	v_and_b32_e32 v82, 0x70, v20
	v_lshl_add_u64 v[16:17], s[30:31], 0, v[12:13]
	v_lshl_add_u64 v[18:19], v[18:19], 0, v[82:83]
	global_load_dwordx4 v[70:73], v[16:17], off nt
	global_load_dwordx4 v[50:53], v[18:19], off offset:3072 nt
	v_min_i32_e32 v18, 63, v104
	v_add_u32_e32 v16, 0xc0, v18
	v_ashrrev_i32_e32 v16, 3, v16
	v_ashrrev_i32_e32 v17, 31, v16
	v_lshlrev_b64 v[90:91], 12, v[16:17]
	v_lshl_add_u64 v[16:17], s[2:3], 0, v[90:91]
	s_add_u32 s2, s30, 0x5a00
	s_addc_u32 s3, s31, 0
	s_or_b32 s0, s0, 32
	s_ashr_i32 s1, s0, 31
	v_lshlrev_b32_e32 v18, 4, v18
	s_lshl_b64 s[0:1], s[0:1], 12
	v_and_b32_e32 v92, 0x70, v18
	v_mov_b32_e32 v93, v83
	s_add_u32 s0, s64, s0
	v_lshl_add_u64 v[16:17], v[16:17], 0, v[92:93]
	s_addc_u32 s1, s65, s1
	v_lshl_add_u64 v[2:3], s[2:3], 0, v[2:3]
	v_lshl_add_u64 v[18:19], s[2:3], 0, v[84:85]
	global_load_dwordx4 v[78:81], v[16:17], off offset:3072 nt
	global_load_dwordx4 v[38:41], v[18:19], off nt
	v_lshl_add_u64 v[6:7], s[2:3], 0, v[6:7]
	global_load_dwordx4 v[34:37], v[2:3], off nt
	global_load_dwordx4 v[30:33], v[6:7], off nt
	v_lshl_add_u64 v[2:3], s[2:3], 0, v[4:5]
	v_lshl_add_u64 v[4:5], s[2:3], 0, v[10:11]
	s_add_u32 s0, s0, s4
	global_load_dwordx4 v[26:29], v[2:3], off nt
	global_load_dwordx4 v[22:25], v[4:5], off nt
	v_lshl_add_u64 v[2:3], s[2:3], 0, v[8:9]
	v_lshl_add_u64 v[4:5], s[2:3], 0, v[14:15]
	s_addc_u32 s1, s1, 0
	global_load_dwordx4 v[18:21], v[2:3], off nt
	global_load_dwordx4 v[14:17], v[4:5], off nt
	v_lshl_add_u64 v[2:3], s[2:3], 0, v[12:13]
	v_lshl_add_u64 v[4:5], s[0:1], 0, v[88:89]
	v_lshl_add_u64 v[4:5], v[4:5], 0, v[82:83]
	global_load_dwordx4 v[10:13], v[2:3], off nt
	global_load_dwordx4 v[6:9], v[4:5], off offset:3072 nt
	v_lshl_add_u64 v[2:3], s[0:1], 0, v[90:91]
	v_lshl_add_u64 v[2:3], v[2:3], 0, v[92:93]
	global_load_dwordx4 v[2:5], v[2:3], off offset:3072 nt
	s_movk_i32 s0, 0x620
	v_cmp_gt_i32_e32 vcc, s0, v114
	v_lshl_add_u32 v82, v104, 4, 0
	s_and_saveexec_b64 s[0:1], vcc
	s_cbranch_execz .LBB0_1133
	v_lshl_add_u64 v[84:85], s[30:31], 0, v[84:85]
	global_load_dwordx4 v[88:91], v[84:85], off nt
	s_waitcnt vmcnt(0)
	ds_write_b128 v82, v[88:91]

.LBB0_1168:
	s_add_i32 s38, s39, 2
	s_cmp_gt_u32 s39, 61
	s_cselect_b64 s[16:17], -1, 0
	s_cmp_lt_u32 s39, 62
	s_cselect_b64 s[2:3], -1, 0
	s_and_b64 s[24:25], s[2:3], exec
	s_cselect_b32 s40, s38, 63
	s_mul_i32 s24, s40, 0x5a00
	s_add_u32 s24, s30, s24
	s_addc_u32 s25, s31, 0
	s_lshl_b32 s40, s40, 5
	s_add_i32 s40, s40, s33
	s_waitcnt vmcnt(10)
	v_lshl_add_u64 v[42:43], s[24:25], 0, v[86:87]
	v_lshl_add_u64 v[44:45], s[24:25], 0, v[88:89]
	s_ashr_i32 s41, s40, 31
	global_load_dwordx4 v[82:85], v[42:43], off nt
	global_load_dwordx4 v[78:81], v[44:45], off nt
	v_lshl_add_u64 v[42:43], s[24:25], 0, v[90:91]
	v_lshl_add_u64 v[44:45], s[24:25], 0, v[92:93]
	s_lshl_b64 s[40:41], s[40:41], 12
	global_load_dwordx4 v[74:77], v[42:43], off nt
	global_load_dwordx4 v[70:73], v[44:45], off nt
	v_lshl_add_u64 v[42:43], s[24:25], 0, v[94:95]
	v_lshl_add_u64 v[44:45], s[24:25], 0, v[96:97]
	global_load_dwordx4 v[62:65], v[42:43], off nt
	global_load_dwordx4 v[58:61], v[44:45], off nt
	v_lshl_add_u64 v[42:43], s[24:25], 0, v[98:99]
	v_lshl_add_u64 v[44:45], s[24:25], 0, v[100:101]
	s_add_u32 s24, s36, s40
	s_addc_u32 s25, s37, s41
	global_load_dwordx4 v[54:57], v[42:43], off nt
	global_load_dwordx4 v[50:53], v[44:45], off nt
	v_lshl_add_u64 v[42:43], s[24:25], 0, v[102:103]
	v_lshl_add_u64 v[44:45], s[24:25], 0, v[106:107]
	v_lshl_add_u64 v[42:43], v[42:43], 0, v[104:105]
	v_lshl_add_u64 v[44:45], v[44:45], 0, v[110:111]
	global_load_dwordx4 v[46:49], v[42:43], off offset:3072 nt
	s_nop 0
	global_load_dwordx4 v[42:45], v[44:45], off offset:3072 nt
	s_and_saveexec_b64 s[24:25], s[0:1]
	s_cbranch_execnz .LBB0_1195
	s_or_b64 exec, exec, s[24:25]
	s_and_saveexec_b64 s[24:25], s[4:5]
	s_cbranch_execnz .LBB0_1196

.LBB0_1181:
	s_or_b64 exec, exec, s[24:25]
	s_min_u32 s24, s39, 60
	s_add_i32 s39, s24, 3
	s_mul_i32 s24, s39, 0x5a00
	s_add_u32 s24, s30, s24
	s_addc_u32 s25, s31, 0
	s_lshl_b32 s39, s39, 5
	s_waitcnt lgkmcnt(0)
	s_barrier
	s_add_i32 s40, s39, s33
	s_waitcnt vmcnt(10)
	v_lshl_add_u64 v[2:3], s[24:25], 0, v[86:87]
	v_lshl_add_u64 v[4:5], s[24:25], 0, v[88:89]
	s_ashr_i32 s41, s40, 31
	global_load_dwordx4 v[38:41], v[2:3], off nt
	global_load_dwordx4 v[34:37], v[4:5], off nt
	v_lshl_add_u64 v[2:3], s[24:25], 0, v[90:91]
	v_lshl_add_u64 v[4:5], s[24:25], 0, v[92:93]
	s_lshl_b64 s[40:41], s[40:41], 12
	global_load_dwordx4 v[30:33], v[2:3], off nt
	global_load_dwordx4 v[26:29], v[4:5], off nt
	v_lshl_add_u64 v[2:3], s[24:25], 0, v[94:95]
	v_lshl_add_u64 v[4:5], s[24:25], 0, v[96:97]
	global_load_dwordx4 v[22:25], v[2:3], off nt
	global_load_dwordx4 v[18:21], v[4:5], off nt
	v_lshl_add_u64 v[2:3], s[24:25], 0, v[98:99]
	v_lshl_add_u64 v[4:5], s[24:25], 0, v[100:101]
	s_add_u32 s24, s36, s40
	s_addc_u32 s25, s37, s41
	global_load_dwordx4 v[14:17], v[2:3], off nt
	global_load_dwordx4 v[10:13], v[4:5], off nt
	v_lshl_add_u64 v[2:3], s[24:25], 0, v[102:103]
	v_lshl_add_u64 v[4:5], s[24:25], 0, v[106:107]
	v_mov_b32_e32 v109, v105
	v_lshl_add_u64 v[2:3], v[2:3], 0, v[104:105]
	v_lshl_add_u64 v[4:5], v[4:5], 0, v[108:109]
	global_load_dwordx4 v[6:9], v[2:3], off offset:3072 nt
	s_nop 0
	global_load_dwordx4 v[2:5], v[4:5], off offset:3072 nt
	s_andn2_b64 vcc, exec, s[2:3]
	s_cbranch_vccnz .LBB0_1167
	s_and_saveexec_b64 s[2:3], s[0:1]
	s_cbranch_execnz .LBB0_1202
	s_or_b64 exec, exec, s[2:3]
	s_and_saveexec_b64 s[2:3], s[4:5]
	s_cbranch_execnz .LBB0_1203
